# bias2 phase hand-written: sh2 rows hoisted to registers, next W row prefetched, 8 wave-sums interleaved (was 8 serial load+butterfly round trips per row)
# speedup vs baseline: 1.0108x; 1.0108x over previous
.LBB0_626:
	s_or_b64 exec, exec, s[0:1]
	s_cmpk_gt_i32 s58, 0x15ff
	s_cbranch_scc1 .LBB0_645
	v_lshlrev_b32_e32 v224, 2, v144
	v_xor_b32_e32 v225, 4, v224
	v_xor_b32_e32 v226, 8, v224
	v_xor_b32_e32 v227, 16, v224
	v_xor_b32_e32 v228, 32, v224
	v_xor_b32_e32 v229, 64, v224
	v_xor_b32_e32 v230, 0x80, v224
	v_lshlrev_b32_e32 v231, 6, v144
	v_lshlrev_b32_e32 v232, 5, v144
	s_add_u32 s2, s54, 0x103000
	s_addc_u32 s3, s55, 0
	global_load_dwordx4 v[0:3], v231, s[2:3]
	global_load_dwordx4 v[4:7], v231, s[2:3] offset:16
	global_load_dwordx4 v[8:11], v231, s[2:3] offset:32
	global_load_dwordx4 v[12:15], v231, s[2:3] offset:48
	s_add_u32 s2, s2, 0x6000
	s_addc_u32 s3, s3, 0
	global_load_dwordx4 v[16:19], v231, s[2:3]
	global_load_dwordx4 v[20:23], v231, s[2:3] offset:16
	global_load_dwordx4 v[24:27], v231, s[2:3] offset:32
	global_load_dwordx4 v[28:31], v231, s[2:3] offset:48
	s_add_u32 s2, s2, 0x6000
	s_addc_u32 s3, s3, 0
	global_load_dwordx4 v[32:35], v231, s[2:3]
	global_load_dwordx4 v[36:39], v231, s[2:3] offset:16
	global_load_dwordx4 v[40:43], v231, s[2:3] offset:32
	global_load_dwordx4 v[44:47], v231, s[2:3] offset:48
	s_add_u32 s2, s2, 0x6000
	s_addc_u32 s3, s3, 0
	global_load_dwordx4 v[48:51], v231, s[2:3]
	global_load_dwordx4 v[52:55], v231, s[2:3] offset:16
	global_load_dwordx4 v[56:59], v231, s[2:3] offset:32
	global_load_dwordx4 v[60:63], v231, s[2:3] offset:48
	s_add_u32 s2, s2, 0x6000
	s_addc_u32 s3, s3, 0
	global_load_dwordx4 v[64:67], v231, s[2:3]
	global_load_dwordx4 v[68:71], v231, s[2:3] offset:16
	global_load_dwordx4 v[72:75], v231, s[2:3] offset:32
	global_load_dwordx4 v[76:79], v231, s[2:3] offset:48
	s_add_u32 s2, s2, 0x6000
	s_addc_u32 s3, s3, 0
	global_load_dwordx4 v[80:83], v231, s[2:3]
	global_load_dwordx4 v[84:87], v231, s[2:3] offset:16
	global_load_dwordx4 v[88:91], v231, s[2:3] offset:32
	global_load_dwordx4 v[92:95], v231, s[2:3] offset:48
	s_add_u32 s2, s2, 0x6000
	s_addc_u32 s3, s3, 0
	global_load_dwordx4 v[96:99], v231, s[2:3]
	global_load_dwordx4 v[100:103], v231, s[2:3] offset:16
	global_load_dwordx4 v[104:107], v231, s[2:3] offset:32
	global_load_dwordx4 v[108:111], v231, s[2:3] offset:48
	s_add_u32 s2, s2, 0x6000
	s_addc_u32 s3, s3, 0
	global_load_dwordx4 v[112:115], v231, s[2:3]
	global_load_dwordx4 v[116:119], v231, s[2:3] offset:16
	global_load_dwordx4 v[120:123], v231, s[2:3] offset:32
	global_load_dwordx4 v[124:127], v231, s[2:3] offset:48
	s_add_u32 s4, s54, 0x1200000
	s_addc_u32 s5, s55, 0
	s_add_u32 s6, s54, 0x140000
	s_addc_u32 s7, s55, 0
	s_mov_b32 s0, s58
	s_lshl_b32 s10, s0, 11
	s_add_u32 s8, s4, s10
	s_addc_u32 s9, s5, 0
	global_load_dwordx4 v[192:195], v232, s[8:9]
	global_load_dwordx4 v[196:199], v232, s[8:9] offset:16
.Lb2_loop:
	s_waitcnt vmcnt(0)
	v_lshlrev_b32_e32 v176, 16, v192
	v_and_b32_e32 v177, 0xffff0000, v192
	v_lshlrev_b32_e32 v178, 16, v193
	v_and_b32_e32 v179, 0xffff0000, v193
	v_lshlrev_b32_e32 v180, 16, v194
	v_and_b32_e32 v181, 0xffff0000, v194
	v_lshlrev_b32_e32 v182, 16, v195
	v_and_b32_e32 v183, 0xffff0000, v195
	v_lshlrev_b32_e32 v184, 16, v196
	v_and_b32_e32 v185, 0xffff0000, v196
	v_lshlrev_b32_e32 v186, 16, v197
	v_and_b32_e32 v187, 0xffff0000, v197
	v_lshlrev_b32_e32 v188, 16, v198
	v_and_b32_e32 v189, 0xffff0000, v198
	v_lshlrev_b32_e32 v190, 16, v199
	v_and_b32_e32 v191, 0xffff0000, v199
	s_add_i32 s1, s0, s75
	s_cmpk_lt_i32 s1, 0x1600
	s_cbranch_scc0 .Lb2_nonext
	s_lshl_b32 s10, s1, 11
	s_add_u32 s8, s4, s10
	s_addc_u32 s9, s5, 0
	global_load_dwordx4 v[192:195], v232, s[8:9]
	global_load_dwordx4 v[196:199], v232, s[8:9] offset:16
.Lb2_nonext:
	v_mul_f32_e32 v208, v4, v180
	v_mul_f32_e32 v209, v5, v181
	v_mul_f32_e32 v210, v6, v182
	v_mul_f32_e32 v211, v7, v183
	v_fmac_f32_e32 v208, v0, v176
	v_fmac_f32_e32 v209, v1, v177
	v_fmac_f32_e32 v210, v2, v178
	v_fmac_f32_e32 v211, v3, v179
	v_fmac_f32_e32 v208, v8, v184
	v_fmac_f32_e32 v209, v9, v185
	v_fmac_f32_e32 v210, v10, v186
	v_fmac_f32_e32 v211, v11, v187
	v_fmac_f32_e32 v208, v12, v188
	v_fmac_f32_e32 v209, v13, v189
	v_fmac_f32_e32 v210, v14, v190
	v_fmac_f32_e32 v211, v15, v191
	v_add_f32_e32 v208, v208, v209
	v_add_f32_e32 v209, v210, v211
	v_add_f32_e32 v200, v208, v209
	v_mul_f32_e32 v208, v20, v180
	v_mul_f32_e32 v209, v21, v181
	v_mul_f32_e32 v210, v22, v182
	v_mul_f32_e32 v211, v23, v183
	v_fmac_f32_e32 v208, v16, v176
	v_fmac_f32_e32 v209, v17, v177
	v_fmac_f32_e32 v210, v18, v178
	v_fmac_f32_e32 v211, v19, v179
	v_fmac_f32_e32 v208, v24, v184
	v_fmac_f32_e32 v209, v25, v185
	v_fmac_f32_e32 v210, v26, v186
	v_fmac_f32_e32 v211, v27, v187
	v_fmac_f32_e32 v208, v28, v188
	v_fmac_f32_e32 v209, v29, v189
	v_fmac_f32_e32 v210, v30, v190
	v_fmac_f32_e32 v211, v31, v191
	v_add_f32_e32 v208, v208, v209
	v_add_f32_e32 v209, v210, v211
	v_add_f32_e32 v201, v208, v209
	v_mul_f32_e32 v208, v36, v180
	v_mul_f32_e32 v209, v37, v181
	v_mul_f32_e32 v210, v38, v182
	v_mul_f32_e32 v211, v39, v183
	v_fmac_f32_e32 v208, v32, v176
	v_fmac_f32_e32 v209, v33, v177
	v_fmac_f32_e32 v210, v34, v178
	v_fmac_f32_e32 v211, v35, v179
	v_fmac_f32_e32 v208, v40, v184
	v_fmac_f32_e32 v209, v41, v185
	v_fmac_f32_e32 v210, v42, v186
	v_fmac_f32_e32 v211, v43, v187
	v_fmac_f32_e32 v208, v44, v188
	v_fmac_f32_e32 v209, v45, v189
	v_fmac_f32_e32 v210, v46, v190
	v_fmac_f32_e32 v211, v47, v191
	v_add_f32_e32 v208, v208, v209
	v_add_f32_e32 v209, v210, v211
	v_add_f32_e32 v202, v208, v209
	v_mul_f32_e32 v208, v52, v180
	v_mul_f32_e32 v209, v53, v181
	v_mul_f32_e32 v210, v54, v182
	v_mul_f32_e32 v211, v55, v183
	v_fmac_f32_e32 v208, v48, v176
	v_fmac_f32_e32 v209, v49, v177
	v_fmac_f32_e32 v210, v50, v178
	v_fmac_f32_e32 v211, v51, v179
	v_fmac_f32_e32 v208, v56, v184
	v_fmac_f32_e32 v209, v57, v185
	v_fmac_f32_e32 v210, v58, v186
	v_fmac_f32_e32 v211, v59, v187
	v_fmac_f32_e32 v208, v60, v188
	v_fmac_f32_e32 v209, v61, v189
	v_fmac_f32_e32 v210, v62, v190
	v_fmac_f32_e32 v211, v63, v191
	v_add_f32_e32 v208, v208, v209
	v_add_f32_e32 v209, v210, v211
	v_add_f32_e32 v203, v208, v209
	v_mul_f32_e32 v208, v68, v180
	v_mul_f32_e32 v209, v69, v181
	v_mul_f32_e32 v210, v70, v182
	v_mul_f32_e32 v211, v71, v183
	v_fmac_f32_e32 v208, v64, v176
	v_fmac_f32_e32 v209, v65, v177
	v_fmac_f32_e32 v210, v66, v178
	v_fmac_f32_e32 v211, v67, v179
	v_fmac_f32_e32 v208, v72, v184
	v_fmac_f32_e32 v209, v73, v185
	v_fmac_f32_e32 v210, v74, v186
	v_fmac_f32_e32 v211, v75, v187
	v_fmac_f32_e32 v208, v76, v188
	v_fmac_f32_e32 v209, v77, v189
	v_fmac_f32_e32 v210, v78, v190
	v_fmac_f32_e32 v211, v79, v191
	v_add_f32_e32 v208, v208, v209
	v_add_f32_e32 v209, v210, v211
	v_add_f32_e32 v204, v208, v209
	v_mul_f32_e32 v208, v84, v180
	v_mul_f32_e32 v209, v85, v181
	v_mul_f32_e32 v210, v86, v182
	v_mul_f32_e32 v211, v87, v183
	v_fmac_f32_e32 v208, v80, v176
	v_fmac_f32_e32 v209, v81, v177
	v_fmac_f32_e32 v210, v82, v178
	v_fmac_f32_e32 v211, v83, v179
	v_fmac_f32_e32 v208, v88, v184
	v_fmac_f32_e32 v209, v89, v185
	v_fmac_f32_e32 v210, v90, v186
	v_fmac_f32_e32 v211, v91, v187
	v_fmac_f32_e32 v208, v92, v188
	v_fmac_f32_e32 v209, v93, v189
	v_fmac_f32_e32 v210, v94, v190
	v_fmac_f32_e32 v211, v95, v191
	v_add_f32_e32 v208, v208, v209
	v_add_f32_e32 v209, v210, v211
	v_add_f32_e32 v205, v208, v209
	v_mul_f32_e32 v208, v100, v180
	v_mul_f32_e32 v209, v101, v181
	v_mul_f32_e32 v210, v102, v182
	v_mul_f32_e32 v211, v103, v183
	v_fmac_f32_e32 v208, v96, v176
	v_fmac_f32_e32 v209, v97, v177
	v_fmac_f32_e32 v210, v98, v178
	v_fmac_f32_e32 v211, v99, v179
	v_fmac_f32_e32 v208, v104, v184
	v_fmac_f32_e32 v209, v105, v185
	v_fmac_f32_e32 v210, v106, v186
	v_fmac_f32_e32 v211, v107, v187
	v_fmac_f32_e32 v208, v108, v188
	v_fmac_f32_e32 v209, v109, v189
	v_fmac_f32_e32 v210, v110, v190
	v_fmac_f32_e32 v211, v111, v191
	v_add_f32_e32 v208, v208, v209
	v_add_f32_e32 v209, v210, v211
	v_add_f32_e32 v206, v208, v209
	v_mul_f32_e32 v208, v116, v180
	v_mul_f32_e32 v209, v117, v181
	v_mul_f32_e32 v210, v118, v182
	v_mul_f32_e32 v211, v119, v183
	v_fmac_f32_e32 v208, v112, v176
	v_fmac_f32_e32 v209, v113, v177
	v_fmac_f32_e32 v210, v114, v178
	v_fmac_f32_e32 v211, v115, v179
	v_fmac_f32_e32 v208, v120, v184
	v_fmac_f32_e32 v209, v121, v185
	v_fmac_f32_e32 v210, v122, v186
	v_fmac_f32_e32 v211, v123, v187
	v_fmac_f32_e32 v208, v124, v188
	v_fmac_f32_e32 v209, v125, v189
	v_fmac_f32_e32 v210, v126, v190
	v_fmac_f32_e32 v211, v127, v191
	v_add_f32_e32 v208, v208, v209
	v_add_f32_e32 v209, v210, v211
	v_add_f32_e32 v207, v208, v209
	ds_bpermute_b32 v212, v225, v200
	ds_bpermute_b32 v213, v225, v201
	ds_bpermute_b32 v214, v225, v202
	ds_bpermute_b32 v215, v225, v203
	ds_bpermute_b32 v216, v225, v204
	ds_bpermute_b32 v217, v225, v205
	ds_bpermute_b32 v218, v225, v206
	ds_bpermute_b32 v219, v225, v207
	s_waitcnt lgkmcnt(7)
	v_add_f32_e32 v200, v200, v212
	s_waitcnt lgkmcnt(6)
	v_add_f32_e32 v201, v201, v213
	s_waitcnt lgkmcnt(5)
	v_add_f32_e32 v202, v202, v214
	s_waitcnt lgkmcnt(4)
	v_add_f32_e32 v203, v203, v215
	s_waitcnt lgkmcnt(3)
	v_add_f32_e32 v204, v204, v216
	s_waitcnt lgkmcnt(2)
	v_add_f32_e32 v205, v205, v217
	s_waitcnt lgkmcnt(1)
	v_add_f32_e32 v206, v206, v218
	s_waitcnt lgkmcnt(0)
	v_add_f32_e32 v207, v207, v219
	ds_bpermute_b32 v212, v226, v200
	ds_bpermute_b32 v213, v226, v201
	ds_bpermute_b32 v214, v226, v202
	ds_bpermute_b32 v215, v226, v203
	ds_bpermute_b32 v216, v226, v204
	ds_bpermute_b32 v217, v226, v205
	ds_bpermute_b32 v218, v226, v206
	ds_bpermute_b32 v219, v226, v207
	s_waitcnt lgkmcnt(7)
	v_add_f32_e32 v200, v200, v212
	s_waitcnt lgkmcnt(6)
	v_add_f32_e32 v201, v201, v213
	s_waitcnt lgkmcnt(5)
	v_add_f32_e32 v202, v202, v214
	s_waitcnt lgkmcnt(4)
	v_add_f32_e32 v203, v203, v215
	s_waitcnt lgkmcnt(3)
	v_add_f32_e32 v204, v204, v216
	s_waitcnt lgkmcnt(2)
	v_add_f32_e32 v205, v205, v217
	s_waitcnt lgkmcnt(1)
	v_add_f32_e32 v206, v206, v218
	s_waitcnt lgkmcnt(0)
	v_add_f32_e32 v207, v207, v219
	ds_bpermute_b32 v212, v227, v200
	ds_bpermute_b32 v213, v227, v201
	ds_bpermute_b32 v214, v227, v202
	ds_bpermute_b32 v215, v227, v203
	ds_bpermute_b32 v216, v227, v204
	ds_bpermute_b32 v217, v227, v205
	ds_bpermute_b32 v218, v227, v206
	ds_bpermute_b32 v219, v227, v207
	s_waitcnt lgkmcnt(7)
	v_add_f32_e32 v200, v200, v212
	s_waitcnt lgkmcnt(6)
	v_add_f32_e32 v201, v201, v213
	s_waitcnt lgkmcnt(5)
	v_add_f32_e32 v202, v202, v214
	s_waitcnt lgkmcnt(4)
	v_add_f32_e32 v203, v203, v215
	s_waitcnt lgkmcnt(3)
	v_add_f32_e32 v204, v204, v216
	s_waitcnt lgkmcnt(2)
	v_add_f32_e32 v205, v205, v217
	s_waitcnt lgkmcnt(1)
	v_add_f32_e32 v206, v206, v218
	s_waitcnt lgkmcnt(0)
	v_add_f32_e32 v207, v207, v219
	ds_bpermute_b32 v212, v228, v200
	ds_bpermute_b32 v213, v228, v201
	ds_bpermute_b32 v214, v228, v202
	ds_bpermute_b32 v215, v228, v203
	ds_bpermute_b32 v216, v228, v204
	ds_bpermute_b32 v217, v228, v205
	ds_bpermute_b32 v218, v228, v206
	ds_bpermute_b32 v219, v228, v207
	s_waitcnt lgkmcnt(7)
	v_add_f32_e32 v200, v200, v212
	s_waitcnt lgkmcnt(6)
	v_add_f32_e32 v201, v201, v213
	s_waitcnt lgkmcnt(5)
	v_add_f32_e32 v202, v202, v214
	s_waitcnt lgkmcnt(4)
	v_add_f32_e32 v203, v203, v215
	s_waitcnt lgkmcnt(3)
	v_add_f32_e32 v204, v204, v216
	s_waitcnt lgkmcnt(2)
	v_add_f32_e32 v205, v205, v217
	s_waitcnt lgkmcnt(1)
	v_add_f32_e32 v206, v206, v218
	s_waitcnt lgkmcnt(0)
	v_add_f32_e32 v207, v207, v219
	ds_bpermute_b32 v212, v229, v200
	ds_bpermute_b32 v213, v229, v201
	ds_bpermute_b32 v214, v229, v202
	ds_bpermute_b32 v215, v229, v203
	ds_bpermute_b32 v216, v229, v204
	ds_bpermute_b32 v217, v229, v205
	ds_bpermute_b32 v218, v229, v206
	ds_bpermute_b32 v219, v229, v207
	s_waitcnt lgkmcnt(7)
	v_add_f32_e32 v200, v200, v212
	s_waitcnt lgkmcnt(6)
	v_add_f32_e32 v201, v201, v213
	s_waitcnt lgkmcnt(5)
	v_add_f32_e32 v202, v202, v214
	s_waitcnt lgkmcnt(4)
	v_add_f32_e32 v203, v203, v215
	s_waitcnt lgkmcnt(3)
	v_add_f32_e32 v204, v204, v216
	s_waitcnt lgkmcnt(2)
	v_add_f32_e32 v205, v205, v217
	s_waitcnt lgkmcnt(1)
	v_add_f32_e32 v206, v206, v218
	s_waitcnt lgkmcnt(0)
	v_add_f32_e32 v207, v207, v219
	ds_bpermute_b32 v212, v230, v200
	ds_bpermute_b32 v213, v230, v201
	ds_bpermute_b32 v214, v230, v202
	ds_bpermute_b32 v215, v230, v203
	ds_bpermute_b32 v216, v230, v204
	ds_bpermute_b32 v217, v230, v205
	ds_bpermute_b32 v218, v230, v206
	ds_bpermute_b32 v219, v230, v207
	s_waitcnt lgkmcnt(7)
	v_add_f32_e32 v200, v200, v212
	s_waitcnt lgkmcnt(6)
	v_add_f32_e32 v201, v201, v213
	s_waitcnt lgkmcnt(5)
	v_add_f32_e32 v202, v202, v214
	s_waitcnt lgkmcnt(4)
	v_add_f32_e32 v203, v203, v215
	s_waitcnt lgkmcnt(3)
	v_add_f32_e32 v204, v204, v216
	s_waitcnt lgkmcnt(2)
	v_add_f32_e32 v205, v205, v217
	s_waitcnt lgkmcnt(1)
	v_add_f32_e32 v206, v206, v218
	s_waitcnt lgkmcnt(0)
	v_add_f32_e32 v207, v207, v219
	v_cmp_eq_u32_e32 vcc, 0, v144
	s_and_saveexec_b64 s[10:11], vcc
	s_lshl_b32 s12, s0, 2
	v_mov_b32_e32 v233, s12
	s_mov_b64 s[12:13], s[6:7]
	global_store_dword v233, v200, s[12:13]
	s_add_u32 s12, s12, 0x5800
	s_addc_u32 s13, s13, 0
	global_store_dword v233, v201, s[12:13]
	s_add_u32 s12, s12, 0x5800
	s_addc_u32 s13, s13, 0
	global_store_dword v233, v202, s[12:13]
	s_add_u32 s12, s12, 0x5800
	s_addc_u32 s13, s13, 0
	global_store_dword v233, v203, s[12:13]
	s_add_u32 s12, s12, 0x5800
	s_addc_u32 s13, s13, 0
	global_store_dword v233, v204, s[12:13]
	s_add_u32 s12, s12, 0x5800
	s_addc_u32 s13, s13, 0
	global_store_dword v233, v205, s[12:13]
	s_add_u32 s12, s12, 0x5800
	s_addc_u32 s13, s13, 0
	global_store_dword v233, v206, s[12:13]
	s_add_u32 s12, s12, 0x5800
	s_addc_u32 s13, s13, 0
	global_store_dword v233, v207, s[12:13]
	s_or_b64 exec, exec, s[10:11]
	s_mov_b32 s0, s1
	s_cmpk_lt_i32 s0, 0x1600
	s_cbranch_scc1 .Lb2_loop
